# prep: q~ / B'^T copy-outs moved from waves 0-6 (serial loop on their critical segment) to wave 7 as two pipelined 8x ds_read_b128 + global_store_dwordx4 batches before its T inversion
# speedup vs baseline: 1.0089x; 1.0089x over previous
; __device__ __forceinline__ void st_bf4(bf16_t* p, f32x4 v) { u32x2 u; u.x = pk_bf16(v[0], v[1]); u.y = pk_bf16(v[2], v[3]); *(u32x2*)p = u; }
; #define MFMA16(a, b, c) __builtin_amdgcn_mfma_f32_16x16x32_bf16(a, b, c, 0, 0, 0)
; __device__ __forceinline__ void phase_prep(const Params& p, unsigned char* shm) {
;     ...
;         if (wid == 7) {
;             tinv_wave(Aab, Tm, TT, ET, E2T, lane);
;         } else {
;             for (int pc = tid; pc < 1024; pc += 448) { const int r = (pc & 511) >> 3, sg = (pc & 7) * 8;
;                 if (pc < 512) *(u32x4*)(p.QG + chbase + r * 64 + sg) = *(const u32x4*)(Qt + r * LD + sg); else *(u32x4*)(p.BPG + chbase + r * 64 + sg) = *(const u32x4*)(BpT + r * LD + sg); }
;             for (int idx = wid; idx < 64; idx += 7) {
;                 const int mat = idx >> 4, nt = (idx >> 2) & 3, ms = idx & 3;
;                 f32x4 c = (f32x4){0.f, 0.f, 0.f, 0.f};
;                 if (mat == 3) {
;                     c = MFMA16(ldfrag(KpT, LD, 16 * nt, 0, fr, fq), ldfrag(VmT, LD, 16 * ms, 0, fr, fq), c);
;                     c = MFMA16(ldfrag(KpT, LD, 16 * nt, 32, fr, fq), ldfrag(VmT, LD, 16 * ms, 32, fr, fq), c);
;                     st_bf4(VKt + (16 * ms + fr) * LD + 16 * nt + 4 * fq, c);
;                 } else {
;                     const bf16_t* asrc = mat == 2 ? Bt : Kt; const bf16_t* bsrc = mat == 0 ? KKt : Qt;
;                     if (ms <= nt) {
;                         c = MFMA16(ldfrag(asrc, LD, 16 * ms, 0, fr, fq), ldfrag(bsrc, LD, 16 * nt, 0, fr, fq), c);
;                         c = MFMA16(ldfrag(asrc, LD, 16 * ms, 32, fr, fq), ldfrag(bsrc, LD, 16 * nt, 32, fr, fq), c);
;                         if (ms == nt) {
; #pragma unroll
;                             for (int j = 0; j < 4; ++j) { const int sx = 4 * fq + j; const bool keep = mat ? (sx <= fr) : (sx < fr); if (!keep) c[j] = 0.f; }
.LBB0_209:
	s_cmp_gt_i32 s71, 63
	v_add_u32_e32 v28, s56, v40
	s_cbranch_scc1 .LBB0_230
	v_or_b32_e32 v24, 2, v139
	v_cmp_le_u32_e64 s[24:25], v24, v185
	v_cmp_lt_u32_e64 s[26:27], v24, v185
	v_or_b32_e32 v24, 3, v139
	v_cmp_le_u32_e64 s[20:21], v139, v185
	v_cmp_lt_u32_e64 s[22:23], v139, v185
	v_cmp_le_u32_e64 s[28:29], v24, v185
	v_cmp_lt_u32_e64 s[30:31], v24, v185
	v_add_u32_e32 v29, s57, v40
	s_mov_b32 s40, s71
	s_branch .LBB0_212

; #define WAVE_SYNC() do { asm volatile("s_waitcnt lgkmcnt(0)" ::: "memory"); __builtin_amdgcn_wave_barrier(); } while (0)
; __device__ __forceinline__ void tinv_wave(const float* Aab, bf16_t* Tm, bf16_t* TT, bf16_t* ET, bf16_t* E2T, int lane) {
;     constexpr int LD = 72;
;     const int fr = lane & 15, fq = lane >> 4;
;     const bf16x8 zf = (bf16x8){0, 0, 0, 0, 0, 0, 0, 0};
;     {
;         const u32x4 z = (u32x4){0u, 0u, 0u, 0u};
; #pragma unroll
;         for (int i = 0; i < 9; ++i) { *(u32x4*)(Tm + lane * LD + i * 8) = z; *(u32x4*)(TT + lane * LD + i * 8) = z; }
;     }
;     WAVE_SYNC();
; __device__ __forceinline__ void phase_prep(const Params& p, unsigned char* shm) {
;     ...
;         if (wid == 7) {
;             tinv_wave(Aab, Tm, TT, ET, E2T, lane);
;         } else {
;             for (int pc = tid; pc < 1024; pc += 448) { const int r = (pc & 511) >> 3, sg = (pc & 7) * 8;
;                 if (pc < 512) *(u32x4*)(p.QG + chbase + r * 64 + sg) = *(const u32x4*)(Qt + r * LD + sg); else *(u32x4*)(p.BPG + chbase + r * 64 + sg) = *(const u32x4*)(BpT + r * LD + sg); }
.LBB0_238:
	s_and_b64 vcc, exec, s[20:21]
	s_cbranch_vccz .LBB0_256
	s_load_dwordx2 s[80:81], s[0:1], 0xe8
	s_load_dwordx2 s[82:83], s[0:1], 0x110
	s_lshl_b64 s[84:85], s[44:45], 1
	v_lshrrev_b32_e32 v203, 3, v68
	v_and_b32_e32 v204, 7, v68
	v_mul_u32_u24_e32 v203, 0x90, v203
	v_lshl_add_u32 v203, v204, 4, v203
	v_lshlrev_b32_e32 v204, 4, v68
	v_add_u32_e32 v206, 0x9000, v203
	v_add_u32_e32 v207, 0x18c00, v203
	v_add_u32_e32 v205, 0x1000, v204
	s_waitcnt lgkmcnt(0)
	s_add_u32 s80, s80, s84
	s_addc_u32 s81, s81, s85
	s_add_u32 s82, s82, s84
	s_addc_u32 s83, s83, s85
	ds_read_b128 v[208:211], v206 offset:0
	ds_read_b128 v[212:215], v206 offset:1152
	ds_read_b128 v[216:219], v206 offset:2304
	ds_read_b128 v[220:223], v206 offset:3456
	ds_read_b128 v[224:227], v206 offset:4608
	ds_read_b128 v[228:231], v206 offset:5760
	ds_read_b128 v[232:235], v206 offset:6912
	ds_read_b128 v[236:239], v206 offset:8064
	s_waitcnt lgkmcnt(7)
	global_store_dwordx4 v204, v[208:211], s[80:81]
	s_waitcnt lgkmcnt(6)
	global_store_dwordx4 v204, v[212:215], s[80:81] offset:1024
	s_waitcnt lgkmcnt(5)
	global_store_dwordx4 v204, v[216:219], s[80:81] offset:2048
	s_waitcnt lgkmcnt(4)
	global_store_dwordx4 v204, v[220:223], s[80:81] offset:3072
	s_waitcnt lgkmcnt(3)
	global_store_dwordx4 v205, v[224:227], s[80:81]
	s_waitcnt lgkmcnt(2)
	global_store_dwordx4 v205, v[228:231], s[80:81] offset:1024
	s_waitcnt lgkmcnt(1)
	global_store_dwordx4 v205, v[232:235], s[80:81] offset:2048
	s_waitcnt lgkmcnt(0)
	global_store_dwordx4 v205, v[236:239], s[80:81] offset:3072
	s_nop 0
	ds_read_b128 v[208:211], v207 offset:0
	ds_read_b128 v[212:215], v207 offset:1152
	ds_read_b128 v[216:219], v207 offset:2304
	ds_read_b128 v[220:223], v207 offset:3456
	ds_read_b128 v[224:227], v207 offset:4608
	ds_read_b128 v[228:231], v207 offset:5760
	ds_read_b128 v[232:235], v207 offset:6912
	ds_read_b128 v[236:239], v207 offset:8064
	s_waitcnt lgkmcnt(7)
	global_store_dwordx4 v204, v[208:211], s[82:83]
	s_waitcnt lgkmcnt(6)
	global_store_dwordx4 v204, v[212:215], s[82:83] offset:1024
	s_waitcnt lgkmcnt(5)
	global_store_dwordx4 v204, v[216:219], s[82:83] offset:2048
	s_waitcnt lgkmcnt(4)
	global_store_dwordx4 v204, v[220:223], s[82:83] offset:3072
	s_waitcnt lgkmcnt(3)
	global_store_dwordx4 v205, v[224:227], s[82:83]
	s_waitcnt lgkmcnt(2)
	global_store_dwordx4 v205, v[228:231], s[82:83] offset:1024
	s_waitcnt lgkmcnt(1)
	global_store_dwordx4 v205, v[232:235], s[82:83] offset:2048
	s_waitcnt lgkmcnt(0)
	global_store_dwordx4 v205, v[236:239], s[82:83] offset:3072
	v_mul_u32_u24_e32 v24, 0x48, v68
	v_lshlrev_b32_e32 v24, 1, v24
	v_add_u32_e32 v25, 0, v24
	v_add_u32_e32 v24, s66, v24
	ds_write_b128 v25, v[192:195] offset:17408
	ds_write_b128 v24, v[192:195]
	ds_write_b128 v25, v[192:195] offset:17424
	ds_write_b128 v24, v[192:195] offset:16
	ds_write_b128 v25, v[192:195] offset:17440
	ds_write_b128 v24, v[192:195] offset:32
	ds_write_b128 v25, v[192:195] offset:17456
	ds_write_b128 v24, v[192:195] offset:48
	ds_write_b128 v25, v[192:195] offset:17472
	ds_write_b128 v24, v[192:195] offset:64
	ds_write_b128 v25, v[192:195] offset:17488
	ds_write_b128 v24, v[192:195] offset:80
	ds_write_b128 v25, v[192:195] offset:17504
	ds_write_b128 v24, v[192:195] offset:96
	ds_write_b128 v25, v[192:195] offset:17520
	ds_write_b128 v24, v[192:195] offset:112
	ds_write_b128 v25, v[192:195] offset:17536
	ds_write_b128 v24, v[192:195] offset:128
	v_mul_u32_u24_e32 v24, 0x110, v141
	v_lshlrev_b32_e32 v25, 2, v141
	v_add3_u32 v69, 0, v24, v25
	s_waitcnt lgkmcnt(0)
	ds_read_b32 v27, v69 offset:272
	ds_read_b64 v[36:37], v69 offset:544
	ds_read_b96 v[24:26], v69 offset:816
	v_cmp_eq_u32_e32 vcc, 0, v185
	s_waitcnt lgkmcnt(0)
	v_mov_b32_e32 v66, v25
	v_cndmask_b32_e64 v30, 0, 1.0, vcc
	v_cmp_eq_u32_e32 vcc, 3, v185
	v_mov_b32_e32 v67, v26
	v_mov_b32_e32 v26, v36
	v_cndmask_b32_e64 v28, 0, 1.0, vcc
	v_cmp_eq_u32_e32 vcc, 1, v185
	v_fma_f32 v87, -v30, v24, v28
	s_nop 0
	v_cndmask_b32_e64 v25, 0, 1.0, vcc
	v_cmp_eq_u32_e32 vcc, 2, v185
	s_nop 1
	v_cndmask_b32_e64 v24, 0, 1.0, vcc
	v_pk_fma_f32 v[32:33], v[30:31], v[26:27], v[24:25] op_sel_hi:[0,1,1] neg_lo:[1,0,0] neg_hi:[1,0,0]
	v_mov_b32_e32 v31, v33
	ds_read_b128 v[26:29], v69 offset:1088
	ds_read_b96 v[34:36], v69 offset:1360
	ds_read_b128 v[42:45], v69 offset:1632
	v_cmp_eq_u32_e32 vcc, 4, v185
	s_waitcnt lgkmcnt(2)
	v_pk_mul_f32 v[24:25], v[30:31], v[26:27]
	v_cndmask_b32_e64 v38, 0, 1.0, vcc
	v_sub_f32_e32 v24, v38, v24
	v_cmp_eq_u32_e32 vcc, 5, v185
	v_sub_f32_e32 v126, v24, v25
	ds_read_b64 v[38:39], v69 offset:1648
	v_cndmask_b32_e64 v24, 0, 1.0, vcc
	v_cmp_eq_u32_e32 vcc, 6, v185
	s_waitcnt lgkmcnt(2)
	v_fma_f32 v143, -v30, v34, v24
	s_waitcnt lgkmcnt(1)
	v_pk_mul_f32 v[24:25], v[30:31], v[42:43]
	v_cndmask_b32_e64 v26, 0, 1.0, vcc
	v_mov_b32_e32 v88, v35
	v_sub_f32_e32 v24, v26, v24
	v_add_u32_e32 v34, 0x77c, v69
	v_add_u32_e32 v35, 0x784, v69
	v_add_u32_e32 v27, 0x55c, v69
	v_sub_f32_e32 v145, v24, v25
	ds_read_b96 v[24:26], v69 offset:1904
	ds_read2_b32 v[42:43], v27 offset1:1
	ds_read2_b32 v[90:91], v34 offset1:1
	ds_read2_b32 v[34:35], v35 offset1:1
	v_cmp_eq_u32_e32 vcc, 7, v185
	v_mov_b32_e32 v89, v36
	s_waitcnt lgkmcnt(3)
	v_mov_b32_e32 v92, v25
	v_cndmask_b32_e64 v27, 0, 1.0, vcc
	v_mov_b32_e32 v93, v26
	v_fma_f32 v190, -v30, v24, v27
	ds_read_b128 v[46:49], v69 offset:2176
	ds_read_b128 v[24:27], v69 offset:2192
	ds_read_b96 v[54:56], v69 offset:2448
	ds_read_b128 v[50:53], v69 offset:2720
	v_cmp_eq_u32_e32 vcc, 8, v185
	v_add_u32_e32 v58, 0x9a4, v69
	s_waitcnt lgkmcnt(3)
; __device__ __forceinline__ void tinv_wave(const float* Aab, bf16_t* Tm, bf16_t* TT, bf16_t* ET, bf16_t* E2T, int lane) {
;     ...
;     {
;         const int q = fq, c = fr; const float* Ab = Aab + (16 * q) * 68 + 16 * q;
;         float d[16];
; #pragma unroll
;         for (int i = 0; i < 16; ++i) {
;             float a = (i == c) ? 1.0f : 0.0f;
; #pragma unroll
;             for (int m = 0; m < i; ++m) a -= Ab[i * 68 + m] * d[m];
;             d[i] = a;
;             if ((i & 3) == 3) __builtin_amdgcn_sched_barrier(0);
;         }
	v_pk_mul_f32 v[46:47], v[30:31], v[46:47]
	v_cndmask_b32_e64 v36, 0, 1.0, vcc
	v_sub_f32_e32 v36, v36, v46
	v_cmp_eq_u32_e32 vcc, 9, v185
	v_sub_f32_e32 v191, v36, v47
	s_waitcnt lgkmcnt(0)
	v_pk_mul_f32 v[50:51], v[30:31], v[50:51]
	v_cndmask_b32_e64 v36, 0, 1.0, vcc
	v_cmp_eq_u32_e32 vcc, 10, v185
	v_fma_f32 v196, -v30, v54, v36
	v_add_u32_e32 v59, 0x9ac, v69
	v_cndmask_b32_e64 v54, 0, 1.0, vcc
	v_sub_f32_e32 v50, v54, v50
	v_add_u32_e32 v60, 0xbbc, v69
	v_mov_b32_e32 v46, v55
	v_mov_b32_e32 v47, v56
	v_add_u32_e32 v36, 0x99c, v69
	v_sub_f32_e32 v197, v50, v51
	v_add_u32_e32 v61, 0xbc4, v69
	v_add_u32_e32 v62, 0xbcc, v69
	v_add_u32_e32 v63, 0xbd4, v69
	ds_read_b64 v[50:51], v69 offset:2752
	ds_read_b128 v[54:57], v69 offset:2736
	ds_read2_b32 v[94:95], v60 offset1:1
	ds_read2_b32 v[96:97], v61 offset1:1
	ds_read2_b32 v[98:99], v59 offset1:1
	ds_read2_b32 v[100:101], v58 offset1:1
	ds_read_b96 v[58:60], v69 offset:2992
	ds_read2_b32 v[102:103], v36 offset1:1
	ds_read2_b32 v[104:105], v62 offset1:1
	ds_read2_b32 v[106:107], v63 offset1:1
	v_cmp_eq_u32_e32 vcc, 11, v185
	s_waitcnt lgkmcnt(3)
	v_mov_b32_e32 v108, v59
	v_mov_b32_e32 v109, v60
	v_cndmask_b32_e64 v36, 0, 1.0, vcc
	v_fma_f32 v198, -v30, v58, v36
	ds_read_b128 v[58:61], v69 offset:3264
	ds_read_b128 v[62:65], v69 offset:3280
	ds_read_b128 v[70:73], v69 offset:3296
	ds_read_b96 v[74:76], v69 offset:3536
	v_cmp_eq_u32_e32 vcc, 12, v185
	v_add_u32_e32 v83, 0x100c, v69
	s_waitcnt lgkmcnt(3)
	v_pk_mul_f32 v[58:59], v[30:31], v[58:59]
	v_cndmask_b32_e64 v36, 0, 1.0, vcc
	v_cmp_eq_u32_e32 vcc, 13, v185
	v_sub_f32_e32 v31, v36, v58
	v_sub_f32_e32 v31, v31, v59
	v_cndmask_b32_e64 v36, 0, 1.0, vcc
	s_waitcnt lgkmcnt(0)
	v_mov_b32_e32 v58, v75
	v_mov_b32_e32 v59, v76
	v_fma_f32 v199, -v30, v74, v36
	ds_read_b128 v[74:77], v69 offset:3808
	ds_read_b96 v[84:86], v69 offset:4080
	ds_read_b128 v[78:81], v69 offset:3824
	v_cmp_eq_u32_e32 vcc, 14, v185
	v_add_u32_e32 v36, 0xddc, v69
	v_fma_f32 v189, -v33, v37, v32
	v_cndmask_b32_e64 v82, 0, 1.0, vcc
	s_waitcnt lgkmcnt(2)
	v_fma_f32 v74, -v30, v74, v82
	v_cndmask_b32_e64 v82, 0, 1.0, s[18:19]
	v_fma_f32 v200, -v33, v75, v74
	ds_read2_b32 v[74:75], v36 offset1:1
	s_waitcnt lgkmcnt(2)
	v_fma_f32 v36, -v30, v84, v82
	v_fma_f32 v201, -v33, v85, v36
	v_add_u32_e32 v36, 0xffc, v69
	v_add_u32_e32 v82, 0x1004, v69
	v_add_u32_e32 v84, 0x1014, v69
	ds_read2_b32 v[110:111], v36 offset1:1
	ds_read2_b32 v[112:113], v82 offset1:1
	ds_read2_b32 v[114:115], v83 offset1:1
	ds_read2_b32 v[116:117], v84 offset1:1
	v_add_u32_e32 v36, 0x101c, v69
	v_mov_b32_e32 v188, v33
	ds_read2_b32 v[118:119], v36 offset1:1
	v_pk_mul_f32 v[36:37], v[188:189], v[66:67]
	v_pk_mul_f32 v[66:67], v[188:189], v[88:89]
	v_add_u32_e32 v154, 0xde4, v69
	v_add_u32_e32 v152, 0xdec, v69
	v_add_u32_e32 v150, 0xdf4, v69
	v_add_u32_e32 v148, 0xdfc, v69
	v_sub_f32_e32 v32, v87, v36
	v_sub_f32_e32 v36, v143, v66
	v_add_u32_e32 v202, 0x1024, v69
	ds_read_b64 v[146:147], v69 offset:3856
	ds_read_b128 v[82:85], v69 offset:3840
	ds_read2_b32 v[148:149], v148 offset1:1
	ds_read2_b32 v[150:151], v150 offset1:1
	ds_read2_b32 v[152:153], v152 offset1:1
	ds_read2_b32 v[154:155], v154 offset1:1
	v_sub_f32_e32 v69, v36, v67
	v_pk_mul_f32 v[66:67], v[188:189], v[92:93]
	v_pk_mul_f32 v[46:47], v[188:189], v[46:47]
	v_sub_f32_e32 v36, v190, v66
	v_sub_f32_e32 v66, v36, v67
	v_sub_f32_e32 v36, v196, v46
	v_sub_f32_e32 v67, v36, v47
	v_pk_mul_f32 v[46:47], v[188:189], v[108:109]
	v_pk_mul_f32 v[58:59], v[188:189], v[58:59]
	v_sub_f32_e32 v36, v198, v46
	v_sub_f32_e32 v87, v36, v47
	v_sub_f32_e32 v47, v32, v37
	v_mov_b32_e32 v46, v189
	v_pk_mul_f32 v[28:29], v[46:47], v[28:29]
	v_pk_mul_f32 v[36:37], v[46:47], v[60:61]
	v_sub_f32_e32 v28, v126, v28
	v_pk_mul_f32 v[48:49], v[46:47], v[48:49]
	v_pk_mul_f32 v[52:53], v[46:47], v[52:53]
	v_pk_mul_f32 v[44:45], v[46:47], v[44:45]
	v_sub_f32_e32 v29, v28, v29
	v_mov_b32_e32 v28, v47
	v_sub_f32_e32 v31, v31, v36
	v_sub_f32_e32 v32, v199, v58
	v_sub_f32_e32 v36, v191, v48
	v_sub_f32_e32 v48, v197, v52
	v_sub_f32_e32 v44, v145, v44
	v_pk_mul_f32 v[42:43], v[28:29], v[42:43]
	v_sub_f32_e32 v32, v32, v59
	v_pk_mul_f32 v[58:59], v[46:47], v[76:77]
	v_sub_f32_e32 v46, v44, v45
	v_sub_f32_e32 v52, v36, v49
	v_sub_f32_e32 v53, v48, v53
	v_sub_f32_e32 v31, v31, v37
	s_waitcnt lgkmcnt(11)
	v_pk_mul_f32 v[36:37], v[28:29], v[74:75]
	v_pk_mul_f32 v[44:45], v[28:29], v[102:103]
	v_sub_f32_e32 v42, v69, v42
	v_pk_mul_f32 v[48:49], v[28:29], v[90:91]
	v_sub_f32_e32 v58, v200, v58
	v_sub_f32_e32 v32, v32, v36
	v_sub_f32_e32 v36, v67, v44
	v_sub_f32_e32 v44, v66, v48
	v_sub_f32_e32 v43, v42, v43
	v_mov_b32_e32 v42, v29
	v_sub_f32_e32 v58, v58, v59
	v_sub_f32_e32 v59, v44, v49
	v_sub_f32_e32 v61, v36, v45
	v_pk_mul_f32 v[44:45], v[28:29], v[94:95]
	v_pk_mul_f32 v[38:39], v[42:43], v[38:39]
	v_fma_f32 v60, -v189, v86, v201
	v_sub_f32_e32 v36, v87, v44
	s_waitcnt lgkmcnt(10)
	v_pk_mul_f32 v[48:49], v[28:29], v[110:111]
	v_pk_mul_f32 v[24:25], v[42:43], v[24:25]
	v_sub_f32_e32 v38, v46, v38
	v_sub_f32_e32 v66, v36, v45
	v_sub_f32_e32 v32, v32, v37
	v_pk_mul_f32 v[36:37], v[42:43], v[78:79]
	v_sub_f32_e32 v28, v60, v48
	v_sub_f32_e32 v24, v52, v24
	v_sub_f32_e32 v39, v38, v39
	v_mov_b32_e32 v38, v43
	v_pk_mul_f32 v[44:45], v[42:43], v[62:63]
	v_sub_f32_e32 v36, v58, v36
	v_sub_f32_e32 v28, v28, v49
	v_pk_mul_f32 v[48:49], v[42:43], v[54:55]
	v_sub_f32_e32 v42, v24, v25
	s_waitcnt lgkmcnt(0)
; __device__ __forceinline__ unsigned pk_bf16(float lo, float hi) { const f32x2 v = (f32x2){lo, hi}; const bf16v2 b = __builtin_convertvector(v, bf16v2); return __builtin_bit_cast(unsigned, b); }
; __device__ __forceinline__ bf16_t f2bf(float f) { return (bf16_t)(pk_bf16(f, 0.f) & 0xffffu); }
; #define LDS_BARRIER() do { asm volatile("s_waitcnt lgkmcnt(0)" ::: "memory"); __builtin_amdgcn_s_barrier(); asm volatile("" ::: "memory"); } while (0)
; #define WAVE_SYNC() do { asm volatile("s_waitcnt lgkmcnt(0)" ::: "memory"); __builtin_amdgcn_wave_barrier(); } while (0)
; #define P() (*(const Params*)(cp = cp_launder(cp)))
; __device__ __forceinline__ void tinv_wave(const float* Aab, bf16_t* Tm, bf16_t* TT, bf16_t* ET, bf16_t* E2T, int lane) {
;     ...
;         const int q = fq, c = fr; const float* Ab = Aab + (16 * q) * 68 + 16 * q;
;         float d[16];
; #pragma unroll
;         for (int i = 0; i < 16; ++i) {
;             float a = (i == c) ? 1.0f : 0.0f;
; #pragma unroll
;             for (int m = 0; m < i; ++m) a -= Ab[i * 68 + m] * d[m];
;             d[i] = a;
;             if ((i & 3) == 3) __builtin_amdgcn_sched_barrier(0);
;         }
;         u32x4 lo, hi;
;         lo.x = pk_bf16(d[0], d[1]); lo.y = pk_bf16(d[2], d[3]); lo.z = pk_bf16(d[4], d[5]); lo.w = pk_bf16(d[6], d[7]);
;         hi.x = pk_bf16(d[8], d[9]); hi.y = pk_bf16(d[10], d[11]); hi.z = pk_bf16(d[12], d[13]); hi.w = pk_bf16(d[14], d[15]);
;         *(u32x4*)(TT + (16 * q + c) * LD + 16 * q) = lo; *(u32x4*)(TT + (16 * q + c) * LD + 16 * q + 8) = hi;
; #pragma unroll
;         for (int i = 0; i < 16; ++i) Tm[(16 * q + i) * LD + 16 * q + c] = f2bf(d[i]);
;     }
;     WAVE_SYNC();
;     LDS_BARRIER();
; #pragma unroll
;     for (int P = 0; P < 2; ++P) {
;         const int lo = 2 * P, hi = 2 * P + 1;
;         const bf16x8 a = fq < 2 ? cvt_frag8(Aab + (16 * hi + fr) * 68 + 16 * lo + 8 * fq) : zf;
;         const bf16x8 b = fq < 2 ? *(const bf16x8*)(TT + (16 * lo + fr) * LD + 16 * lo + 8 * fq) : zf;
	v_pk_mul_f32 v[24:25], v[38:39], v[154:155]
	v_pk_mul_f32 v[34:35], v[38:39], v[34:35]
	v_sub_f32_e32 v31, v31, v44
	v_sub_f32_e32 v44, v53, v48
	v_sub_f32_e32 v24, v32, v24
	v_sub_f32_e32 v32, v36, v37
	v_pk_mul_f32 v[36:37], v[38:39], v[100:101]
	v_sub_f32_e32 v34, v59, v34
	v_sub_f32_e32 v46, v44, v49
	v_sub_f32_e32 v31, v31, v45
	v_sub_f32_e32 v36, v61, v36
	v_sub_f32_e32 v45, v34, v35
	v_mov_b32_e32 v44, v39
	v_sub_f32_e32 v52, v36, v37
	v_pk_mul_f32 v[36:37], v[38:39], v[96:97]
	v_pk_mul_f32 v[26:27], v[44:45], v[26:27]
	v_sub_f32_e32 v36, v66, v36
	v_sub_f32_e32 v26, v42, v26
	v_sub_f32_e32 v53, v36, v37
	v_pk_mul_f32 v[34:35], v[44:45], v[64:65]
	v_pk_mul_f32 v[36:37], v[38:39], v[112:113]
	v_sub_f32_e32 v49, v26, v27
	v_mov_b32_e32 v48, v45
	v_sub_f32_e32 v31, v31, v34
	v_sub_f32_e32 v34, v24, v25
	v_pk_mul_f32 v[24:25], v[44:45], v[80:81]
	v_sub_f32_e32 v28, v28, v36
	v_pk_mul_f32 v[26:27], v[48:49], v[152:153]
	v_sub_f32_e32 v24, v32, v24
	v_sub_f32_e32 v28, v28, v37
	v_pk_mul_f32 v[36:37], v[44:45], v[56:57]
	v_sub_f32_e32 v31, v31, v35
	v_sub_f32_e32 v26, v34, v26
	v_pk_mul_f32 v[34:35], v[48:49], v[104:105]
	v_sub_f32_e32 v32, v46, v36
	v_sub_f32_e32 v36, v24, v25
	v_pk_mul_f32 v[24:25], v[48:49], v[98:99]
	v_sub_f32_e32 v34, v53, v34
	v_sub_f32_e32 v32, v32, v37
	v_sub_f32_e32 v24, v52, v24
	v_sub_f32_e32 v37, v34, v35
	v_pk_mul_f32 v[34:35], v[48:49], v[114:115]
	v_sub_f32_e32 v53, v24, v25
	v_mov_b32_e32 v52, v49
	v_sub_f32_e32 v28, v28, v34
	v_sub_f32_e32 v28, v28, v35
	v_pk_mul_f32 v[34:35], v[52:53], v[50:51]
	v_pk_mul_f32 v[24:25], v[52:53], v[70:71]
	v_sub_f32_e32 v32, v32, v34
	v_sub_f32_e32 v24, v31, v24
	v_sub_f32_e32 v31, v26, v27
	v_pk_mul_f32 v[26:27], v[52:53], v[82:83]
	v_sub_f32_e32 v51, v32, v35
	v_mov_b32_e32 v50, v53
	v_sub_f32_e32 v26, v36, v26
	v_sub_f32_e32 v34, v24, v25
	v_pk_mul_f32 v[24:25], v[50:51], v[150:151]
	v_mov_b32_e32 v54, v51
	v_sub_f32_e32 v24, v31, v24
	v_sub_f32_e32 v31, v26, v27
	v_pk_mul_f32 v[26:27], v[50:51], v[106:107]
	v_sub_f32_e32 v32, v24, v25
	v_sub_f32_e32 v26, v37, v26
	v_sub_f32_e32 v55, v26, v27
	v_pk_mul_f32 v[26:27], v[54:55], v[72:73]
	v_mov_b32_e32 v56, v55
	v_sub_f32_e32 v26, v34, v26
	v_sub_f32_e32 v57, v26, v27
	v_pk_mul_f32 v[26:27], v[56:57], v[148:149]
	v_pk_mul_f32 v[24:25], v[54:55], v[84:85]
	v_sub_f32_e32 v26, v32, v26
	v_sub_f32_e32 v59, v26, v27
	ds_read2_b32 v[26:27], v202 offset1:1
	v_sub_f32_e32 v24, v31, v24
	v_pk_mul_f32 v[34:35], v[50:51], v[116:117]
	v_mov_b32_e32 v58, v57
	v_sub_f32_e32 v28, v28, v34
	v_sub_f32_e32 v31, v24, v25
	v_pk_mul_f32 v[24:25], v[58:59], v[146:147]
	v_sub_f32_e32 v28, v28, v35
	v_sub_f32_e32 v24, v31, v24
	v_pk_mul_f32 v[34:35], v[56:57], v[118:119]
	v_sub_f32_e32 v61, v24, v25
	v_sub_f32_e32 v28, v28, v34
	v_mov_b32_e32 v60, v59
	v_sub_f32_e32 v28, v28, v35
	s_waitcnt lgkmcnt(0)
	v_pk_mul_f32 v[24:25], v[60:61], v[26:27]
	s_nop 0
	v_sub_f32_e32 v24, v28, v24
	v_sub_f32_e32 v28, v24, v25
	v_mul_u32_u24_e32 v31, 0x90, v68
	v_lshlrev_b32_e32 v32, 1, v141
	v_cvt_pk_bf16_f32 v24, v30, v33
	v_cvt_pk_bf16_f32 v25, v189, v47
	v_cvt_pk_bf16_f32 v26, v29, v43
	v_cvt_pk_bf16_f32 v27, v39, v45
	v_add3_u32 v31, s66, v31, v32
	v_cvt_pk_bf16_f32 v34, v49, v53
	v_cvt_pk_bf16_f32 v35, v51, v55
	v_cvt_pk_bf16_f32 v36, v57, v59
	v_cvt_pk_bf16_f32 v37, v61, v28
	ds_write_b128 v31, v[24:27]
	ds_write_b128 v31, v[34:37] offset:16
	v_lshlrev_b32_e32 v24, 1, v185
	v_add3_u32 v24, 0, v32, v24
	v_cvt_pk_bf16_f32 v25, v30, s0
	v_mad_u32_u24 v26, v141, s50, v24
	ds_write_b16 v26, v25 offset:17408
	v_cvt_pk_bf16_f32 v25, v33, s0
	ds_write_b16 v26, v25 offset:17552
	v_cvt_pk_bf16_f32 v25, v189, s0
	ds_write_b16 v26, v25 offset:17696
	v_cvt_pk_bf16_f32 v25, v47, s0
	ds_write_b16 v26, v25 offset:17840
	v_cvt_pk_bf16_f32 v25, v29, s0
	ds_write_b16 v26, v25 offset:17984
	v_cvt_pk_bf16_f32 v25, v43, s0
	ds_write_b16 v26, v25 offset:18128
	v_cvt_pk_bf16_f32 v25, v39, s0
	ds_write_b16 v26, v25 offset:18272
	v_cvt_pk_bf16_f32 v25, v45, s0
	ds_write_b16 v26, v25 offset:18416
	v_cvt_pk_bf16_f32 v25, v49, s0
	ds_write_b16 v26, v25 offset:18560
	v_cvt_pk_bf16_f32 v25, v53, s0
	ds_write_b16 v26, v25 offset:18704
	v_cvt_pk_bf16_f32 v25, v51, s0
	ds_write_b16 v26, v25 offset:18848
	v_cvt_pk_bf16_f32 v25, v55, s0
	ds_write_b16 v26, v25 offset:18992
	v_cvt_pk_bf16_f32 v25, v57, s0
	ds_write_b16 v26, v25 offset:19136
	v_cvt_pk_bf16_f32 v25, v59, s0
	ds_write_b16 v26, v25 offset:19280
	v_cvt_pk_bf16_f32 v25, v61, s0
	ds_write_b16 v26, v25 offset:19424
	v_or_b32_e32 v26, 15, v68
	v_cvt_pk_bf16_f32 v25, v28, s0
	v_mad_u32_u24 v24, v26, s50, v24
	ds_write_b16 v24, v25 offset:17408
	s_waitcnt lgkmcnt(0)
	s_waitcnt lgkmcnt(0)
	s_barrier
	v_cmp_gt_u32_e32 vcc, 32, v68
	v_lshlrev_b32_e32 v35, 5, v137
	v_mov_b32_e32 v24, 0
	v_mov_b32_e32 v28, 0
	v_mov_b32_e32 v29, 0
	v_mov_b32_e32 v30, 0
	v_mov_b32_e32 v31, 0
	s_and_saveexec_b64 s[18:19], vcc
	s_cbranch_execz .LBB0_241
	v_or_b32_e32 v25, 16, v68
	v_mul_u32_u24_e32 v25, 0x110, v25
	v_add3_u32 v25, 0, v25, v35
	ds_read_b128 v[28:31], v25
	ds_read_b128 v[36:39], v25 offset:16
	s_waitcnt lgkmcnt(1)
	v_cvt_pk_bf16_f32 v28, v28, v29
	v_cvt_pk_bf16_f32 v29, v30, v31
	s_waitcnt lgkmcnt(0)
	v_cvt_pk_bf16_f32 v30, v36, v37
	v_cvt_pk_bf16_f32 v31, v38, v39
